# non-temporal stores for the final normalized output in the fused epilogue
# speedup vs baseline: 1.0064x; 1.0006x over previous
.Lfn_goA:
	s_and_saveexec_b64 s[44:45], s[38:39]
	global_load_dwordx2 v[238:239], v[198:199], off offset:1024 sc1
	global_load_dwordx2 v[240:241], v[198:199], off offset:1152 sc1
	global_load_dwordx2 v[242:243], v[198:199], off offset:1280 sc1
	global_load_dwordx2 v[244:245], v[198:199], off offset:1408 sc1
	s_mov_b64 exec, s[44:45]
	v_add_f64 v[230:231], v[230:231], -s[0:1]
	v_add_f64 v[232:233], v[232:233], -s[0:1]
	v_add_f64 v[234:235], v[234:235], -s[0:1]
	v_add_f64 v[236:237], v[236:237], -s[0:1]
	v_cvt_f32_f64_e32 v230, v[230:231]
	v_cvt_f32_f64_e32 v232, v[232:233]
	v_cvt_f32_f64_e32 v234, v[234:235]
	v_cvt_f32_f64_e32 v236, v[236:237]
	s_nop 1
	ds_bpermute_b32 v230, v0, v230
	ds_bpermute_b32 v232, v0, v232
	ds_bpermute_b32 v234, v0, v234
	ds_bpermute_b32 v236, v0, v236
	s_waitcnt lgkmcnt(0)
	v_fmamk_f32 v230, v230, 0x3a000000, v207
	s_nop 0
	v_rsq_f32_e32 v230, v230
	s_nop 0
	v_pk_mul_f32 v[126:127], v[126:127], v[230:231] op_sel_hi:[1,0]
	v_pk_mul_f32 v[126:127], v[182:183], v[126:127]
	v_pk_mul_f32 v[128:129], v[128:129], v[230:231] op_sel_hi:[1,0]
	v_pk_mul_f32 v[128:129], v[184:185], v[128:129]
	v_pk_mul_f32 v[122:123], v[122:123], v[230:231] op_sel_hi:[1,0]
	v_pk_mul_f32 v[122:123], v[186:187], v[122:123]
	v_pk_mul_f32 v[124:125], v[124:125], v[230:231] op_sel_hi:[1,0]
	v_pk_mul_f32 v[124:125], v[188:189], v[124:125]
	v_pk_mul_f32 v[118:119], v[118:119], v[230:231] op_sel_hi:[1,0]
	v_pk_mul_f32 v[118:119], v[190:191], v[118:119]
	v_pk_mul_f32 v[120:121], v[120:121], v[230:231] op_sel_hi:[1,0]
	v_pk_mul_f32 v[120:121], v[192:193], v[120:121]
	v_pk_mul_f32 v[114:115], v[114:115], v[230:231] op_sel_hi:[1,0]
	v_pk_mul_f32 v[114:115], v[194:195], v[114:115]
	v_pk_mul_f32 v[116:117], v[116:117], v[230:231] op_sel_hi:[1,0]
	v_pk_mul_f32 v[116:117], v[196:197], v[116:117]
	global_store_dwordx4 v[248:249], v[126:129], off nt
	global_store_dwordx4 v[248:249], v[122:125], off offset:16 nt
	global_store_dwordx4 v[248:249], v[118:121], off offset:128 nt
	global_store_dwordx4 v[248:249], v[114:117], off offset:144 nt
	v_fmamk_f32 v232, v232, 0x3a000000, v207
	s_nop 0
	v_rsq_f32_e32 v232, v232
	s_nop 0
	v_pk_mul_f32 v[110:111], v[110:111], v[232:233] op_sel_hi:[1,0]
	v_pk_mul_f32 v[110:111], v[182:183], v[110:111]
	v_pk_mul_f32 v[112:113], v[112:113], v[232:233] op_sel_hi:[1,0]
	v_pk_mul_f32 v[112:113], v[184:185], v[112:113]
	v_pk_mul_f32 v[106:107], v[106:107], v[232:233] op_sel_hi:[1,0]
	v_pk_mul_f32 v[106:107], v[186:187], v[106:107]
	v_pk_mul_f32 v[108:109], v[108:109], v[232:233] op_sel_hi:[1,0]
	v_pk_mul_f32 v[108:109], v[188:189], v[108:109]
	v_pk_mul_f32 v[102:103], v[102:103], v[232:233] op_sel_hi:[1,0]
	v_pk_mul_f32 v[102:103], v[190:191], v[102:103]
	v_pk_mul_f32 v[104:105], v[104:105], v[232:233] op_sel_hi:[1,0]
	v_pk_mul_f32 v[104:105], v[192:193], v[104:105]
	v_pk_mul_f32 v[98:99], v[98:99], v[232:233] op_sel_hi:[1,0]
	v_pk_mul_f32 v[98:99], v[194:195], v[98:99]
	v_pk_mul_f32 v[100:101], v[100:101], v[232:233] op_sel_hi:[1,0]
	v_pk_mul_f32 v[100:101], v[196:197], v[100:101]
	s_mov_b64 s[42:43], 0x20000
	v_lshl_add_u64 v[180:181], v[248:249], 0, s[42:43]
	global_store_dwordx4 v[180:181], v[110:113], off nt
	global_store_dwordx4 v[180:181], v[106:109], off offset:16 nt
	global_store_dwordx4 v[180:181], v[102:105], off offset:128 nt
	global_store_dwordx4 v[180:181], v[98:101], off offset:144 nt
	v_fmamk_f32 v234, v234, 0x3a000000, v207
	s_nop 0
	v_rsq_f32_e32 v234, v234
	s_nop 0
	v_pk_mul_f32 v[94:95], v[94:95], v[234:235] op_sel_hi:[1,0]
	v_pk_mul_f32 v[94:95], v[182:183], v[94:95]
	v_pk_mul_f32 v[96:97], v[96:97], v[234:235] op_sel_hi:[1,0]
	v_pk_mul_f32 v[96:97], v[184:185], v[96:97]
	v_pk_mul_f32 v[90:91], v[90:91], v[234:235] op_sel_hi:[1,0]
	v_pk_mul_f32 v[90:91], v[186:187], v[90:91]
	v_pk_mul_f32 v[92:93], v[92:93], v[234:235] op_sel_hi:[1,0]
	v_pk_mul_f32 v[92:93], v[188:189], v[92:93]
	v_pk_mul_f32 v[86:87], v[86:87], v[234:235] op_sel_hi:[1,0]
	v_pk_mul_f32 v[86:87], v[190:191], v[86:87]
	v_pk_mul_f32 v[88:89], v[88:89], v[234:235] op_sel_hi:[1,0]
	v_pk_mul_f32 v[88:89], v[192:193], v[88:89]
	v_pk_mul_f32 v[82:83], v[82:83], v[234:235] op_sel_hi:[1,0]
	v_pk_mul_f32 v[82:83], v[194:195], v[82:83]
	v_pk_mul_f32 v[84:85], v[84:85], v[234:235] op_sel_hi:[1,0]
	v_pk_mul_f32 v[84:85], v[196:197], v[84:85]
	s_mov_b64 s[42:43], 0x40000
	v_lshl_add_u64 v[180:181], v[248:249], 0, s[42:43]
	global_store_dwordx4 v[180:181], v[94:97], off nt
	global_store_dwordx4 v[180:181], v[90:93], off offset:16 nt
	global_store_dwordx4 v[180:181], v[86:89], off offset:128 nt
	global_store_dwordx4 v[180:181], v[82:85], off offset:144 nt
	v_fmamk_f32 v236, v236, 0x3a000000, v207
	s_nop 0
	v_rsq_f32_e32 v236, v236
	s_nop 0
	v_pk_mul_f32 v[78:79], v[78:79], v[236:237] op_sel_hi:[1,0]
	v_pk_mul_f32 v[78:79], v[182:183], v[78:79]
	v_pk_mul_f32 v[80:81], v[80:81], v[236:237] op_sel_hi:[1,0]
	v_pk_mul_f32 v[80:81], v[184:185], v[80:81]
	v_pk_mul_f32 v[74:75], v[74:75], v[236:237] op_sel_hi:[1,0]
	v_pk_mul_f32 v[74:75], v[186:187], v[74:75]
	v_pk_mul_f32 v[76:77], v[76:77], v[236:237] op_sel_hi:[1,0]
	v_pk_mul_f32 v[76:77], v[188:189], v[76:77]
	v_pk_mul_f32 v[70:71], v[70:71], v[236:237] op_sel_hi:[1,0]
	v_pk_mul_f32 v[70:71], v[190:191], v[70:71]
	v_pk_mul_f32 v[72:73], v[72:73], v[236:237] op_sel_hi:[1,0]
	v_pk_mul_f32 v[72:73], v[192:193], v[72:73]
	v_pk_mul_f32 v[66:67], v[66:67], v[236:237] op_sel_hi:[1,0]
	v_pk_mul_f32 v[66:67], v[194:195], v[66:67]
	v_pk_mul_f32 v[68:69], v[68:69], v[236:237] op_sel_hi:[1,0]
	v_pk_mul_f32 v[68:69], v[196:197], v[68:69]
	s_mov_b64 s[42:43], 0x60000
	v_lshl_add_u64 v[180:181], v[248:249], 0, s[42:43]
	global_store_dwordx4 v[180:181], v[78:81], off nt
	global_store_dwordx4 v[180:181], v[74:77], off offset:16 nt
	global_store_dwordx4 v[180:181], v[70:73], off offset:128 nt
	global_store_dwordx4 v[180:181], v[66:69], off offset:144 nt
	s_waitcnt vmcnt(16)
	s_and_saveexec_b64 s[44:45], s[38:39]
	v_min_f64 v[250:251], v[238:239], v[240:241]
	v_min_f64 v[250:251], v[250:251], v[242:243]
	v_min_f64 v[250:251], v[250:251], v[244:245]
	s_nop 1
	v_cmp_gt_f64_e32 vcc, s[0:1], v[250:251]
	s_mov_b64 exec, s[44:45]
	s_cbranch_vccz .Lfn_goB

.Lfn_goB:
	v_add_f64 v[238:239], v[238:239], -s[0:1]
	v_add_f64 v[240:241], v[240:241], -s[0:1]
	v_add_f64 v[242:243], v[242:243], -s[0:1]
	v_add_f64 v[244:245], v[244:245], -s[0:1]
	v_cvt_f32_f64_e32 v238, v[238:239]
	v_cvt_f32_f64_e32 v240, v[240:241]
	v_cvt_f32_f64_e32 v242, v[242:243]
	v_cvt_f32_f64_e32 v244, v[244:245]
	s_nop 1
	ds_bpermute_b32 v238, v0, v238
	ds_bpermute_b32 v240, v0, v240
	ds_bpermute_b32 v242, v0, v242
	ds_bpermute_b32 v244, v0, v244
	s_waitcnt lgkmcnt(0)
	v_fmamk_f32 v238, v238, 0x3a000000, v207
	s_nop 0
	v_rsq_f32_e32 v238, v238
	s_nop 0
	v_pk_mul_f32 v[62:63], v[62:63], v[238:239] op_sel_hi:[1,0]
	v_pk_mul_f32 v[62:63], v[182:183], v[62:63]
	v_pk_mul_f32 v[64:65], v[64:65], v[238:239] op_sel_hi:[1,0]
	v_pk_mul_f32 v[64:65], v[184:185], v[64:65]
	v_pk_mul_f32 v[58:59], v[58:59], v[238:239] op_sel_hi:[1,0]
	v_pk_mul_f32 v[58:59], v[186:187], v[58:59]
	v_pk_mul_f32 v[60:61], v[60:61], v[238:239] op_sel_hi:[1,0]
	v_pk_mul_f32 v[60:61], v[188:189], v[60:61]
	v_pk_mul_f32 v[54:55], v[54:55], v[238:239] op_sel_hi:[1,0]
	v_pk_mul_f32 v[54:55], v[190:191], v[54:55]
	v_pk_mul_f32 v[56:57], v[56:57], v[238:239] op_sel_hi:[1,0]
	v_pk_mul_f32 v[56:57], v[192:193], v[56:57]
	v_pk_mul_f32 v[50:51], v[50:51], v[238:239] op_sel_hi:[1,0]
	v_pk_mul_f32 v[50:51], v[194:195], v[50:51]
	v_pk_mul_f32 v[52:53], v[52:53], v[238:239] op_sel_hi:[1,0]
	v_pk_mul_f32 v[52:53], v[196:197], v[52:53]
	s_mov_b64 s[42:43], 0x100000
	v_lshl_add_u64 v[180:181], v[248:249], 0, s[42:43]
	global_store_dwordx4 v[180:181], v[62:65], off nt
	global_store_dwordx4 v[180:181], v[58:61], off offset:16 nt
	global_store_dwordx4 v[180:181], v[54:57], off offset:128 nt
	global_store_dwordx4 v[180:181], v[50:53], off offset:144 nt
	v_fmamk_f32 v240, v240, 0x3a000000, v207
	s_nop 0
	v_rsq_f32_e32 v240, v240
	s_nop 0
	v_pk_mul_f32 v[46:47], v[46:47], v[240:241] op_sel_hi:[1,0]
	v_pk_mul_f32 v[46:47], v[182:183], v[46:47]
	v_pk_mul_f32 v[48:49], v[48:49], v[240:241] op_sel_hi:[1,0]
	v_pk_mul_f32 v[48:49], v[184:185], v[48:49]
	v_pk_mul_f32 v[42:43], v[42:43], v[240:241] op_sel_hi:[1,0]
	v_pk_mul_f32 v[42:43], v[186:187], v[42:43]
	v_pk_mul_f32 v[44:45], v[44:45], v[240:241] op_sel_hi:[1,0]
	v_pk_mul_f32 v[44:45], v[188:189], v[44:45]
	v_pk_mul_f32 v[38:39], v[38:39], v[240:241] op_sel_hi:[1,0]
	v_pk_mul_f32 v[38:39], v[190:191], v[38:39]
	v_pk_mul_f32 v[40:41], v[40:41], v[240:241] op_sel_hi:[1,0]
	v_pk_mul_f32 v[40:41], v[192:193], v[40:41]
	v_pk_mul_f32 v[34:35], v[34:35], v[240:241] op_sel_hi:[1,0]
	v_pk_mul_f32 v[34:35], v[194:195], v[34:35]
	v_pk_mul_f32 v[36:37], v[36:37], v[240:241] op_sel_hi:[1,0]
	v_pk_mul_f32 v[36:37], v[196:197], v[36:37]
	s_mov_b64 s[42:43], 0x120000
	v_lshl_add_u64 v[180:181], v[248:249], 0, s[42:43]
	global_store_dwordx4 v[180:181], v[46:49], off nt
	global_store_dwordx4 v[180:181], v[42:45], off offset:16 nt
	global_store_dwordx4 v[180:181], v[38:41], off offset:128 nt
	global_store_dwordx4 v[180:181], v[34:37], off offset:144 nt
	v_fmamk_f32 v242, v242, 0x3a000000, v207
	s_nop 0
	v_rsq_f32_e32 v242, v242
	s_nop 0
	v_pk_mul_f32 v[30:31], v[30:31], v[242:243] op_sel_hi:[1,0]
	v_pk_mul_f32 v[30:31], v[182:183], v[30:31]
	v_pk_mul_f32 v[32:33], v[32:33], v[242:243] op_sel_hi:[1,0]
	v_pk_mul_f32 v[32:33], v[184:185], v[32:33]
	v_pk_mul_f32 v[26:27], v[26:27], v[242:243] op_sel_hi:[1,0]
	v_pk_mul_f32 v[26:27], v[186:187], v[26:27]
	v_pk_mul_f32 v[28:29], v[28:29], v[242:243] op_sel_hi:[1,0]
	v_pk_mul_f32 v[28:29], v[188:189], v[28:29]
	v_pk_mul_f32 v[22:23], v[22:23], v[242:243] op_sel_hi:[1,0]
	v_pk_mul_f32 v[22:23], v[190:191], v[22:23]
	v_pk_mul_f32 v[24:25], v[24:25], v[242:243] op_sel_hi:[1,0]
	v_pk_mul_f32 v[24:25], v[192:193], v[24:25]
	v_pk_mul_f32 v[18:19], v[18:19], v[242:243] op_sel_hi:[1,0]
	v_pk_mul_f32 v[18:19], v[194:195], v[18:19]
	v_pk_mul_f32 v[20:21], v[20:21], v[242:243] op_sel_hi:[1,0]
	v_pk_mul_f32 v[20:21], v[196:197], v[20:21]
	s_mov_b64 s[42:43], 0x140000
	v_lshl_add_u64 v[180:181], v[248:249], 0, s[42:43]
	global_store_dwordx4 v[180:181], v[30:33], off nt
	global_store_dwordx4 v[180:181], v[26:29], off offset:16 nt
	global_store_dwordx4 v[180:181], v[22:25], off offset:128 nt
	global_store_dwordx4 v[180:181], v[18:21], off offset:144 nt
	v_fmamk_f32 v244, v244, 0x3a000000, v207
	s_nop 0
	v_rsq_f32_e32 v244, v244
	s_nop 0
	v_pk_mul_f32 v[14:15], v[14:15], v[244:245] op_sel_hi:[1,0]
	v_pk_mul_f32 v[14:15], v[182:183], v[14:15]
	v_pk_mul_f32 v[16:17], v[16:17], v[244:245] op_sel_hi:[1,0]
	v_pk_mul_f32 v[16:17], v[184:185], v[16:17]
	v_pk_mul_f32 v[10:11], v[10:11], v[244:245] op_sel_hi:[1,0]
	v_pk_mul_f32 v[10:11], v[186:187], v[10:11]
	v_pk_mul_f32 v[12:13], v[12:13], v[244:245] op_sel_hi:[1,0]
	v_pk_mul_f32 v[12:13], v[188:189], v[12:13]
	v_pk_mul_f32 v[6:7], v[6:7], v[244:245] op_sel_hi:[1,0]
	v_pk_mul_f32 v[6:7], v[190:191], v[6:7]
	v_pk_mul_f32 v[8:9], v[8:9], v[244:245] op_sel_hi:[1,0]
	v_pk_mul_f32 v[8:9], v[192:193], v[8:9]
	v_pk_mul_f32 v[2:3], v[2:3], v[244:245] op_sel_hi:[1,0]
	v_pk_mul_f32 v[2:3], v[194:195], v[2:3]
	v_pk_mul_f32 v[4:5], v[4:5], v[244:245] op_sel_hi:[1,0]
	v_pk_mul_f32 v[4:5], v[196:197], v[4:5]
	s_mov_b64 s[42:43], 0x160000
	v_lshl_add_u64 v[180:181], v[248:249], 0, s[42:43]
	global_store_dwordx4 v[180:181], v[14:17], off nt
	global_store_dwordx4 v[180:181], v[10:13], off offset:16 nt
	global_store_dwordx4 v[180:181], v[6:9], off offset:128 nt
	global_store_dwordx4 v[180:181], v[2:5], off offset:144 nt
	s_branch .LBB0_487
